# MLA-only V tile LDS layout permuted at store so V fragments read as one ds_read_b128
# speedup vs baseline: 1.0121x; 1.0028x over previous
; #define A_STORE(P, buf) { *reinterpret_cast<uint4*>(ks0 + (buf) * BUF_BYTES) = P##k0; *reinterpret_cast<uint4*>(ks1 + (buf) * BUF_BYTES) = P##k1; \
;     if (NKC == 3) *reinterpret_cast<uint4*>(ks2 + (buf) * BUF_BYTES) = P##k2;                                        \
;     *reinterpret_cast<uint4*>(vs0 + (buf) * BUF_BYTES) = P##v0; *reinterpret_cast<uint4*>(vs1 + (buf) * BUF_BYTES) = P##v1; }
; template <int KS, bool MASK, int NC, bool SH>
; DI void attn_block(const u16* Qp, int qstride, const u16* Kp, int kstride, const u16* Vtp, const u64* maskp, int nkt_w, int nkt_max,
;                    const u16* gatep, int gstride, u16* outp, int ostride, char* lds, int tid) {
;     ...
;   uint4 xk0, xk1, xk2, xv0, xv1, yk0, yk1, yk2, yv0, yv1;
;   xk2 = yk2 = make_uint4(0, 0, 0, 0);
;   const int c0 = tid, c1 = tid + 256, c2 = tid + 512;
;   const u16* kg0 = Kp + (size_t)(c0 / KCH) * kstride + (c0 % KCH) * 8;
;   const u16* kg1 = Kp + (size_t)(c1 / KCH) * kstride + (c1 % KCH) * 8;
;   const u16* kg2 = Kp + (size_t)(c2 / KCH) * kstride + (c2 % KCH) * 8;
;   const u16* vg0 = Vtp + (size_t)(c0 >> 3) * S + (c0 & 7) * 8;
;   const u16* vg1 = Vtp + (size_t)(c1 >> 3) * S + (c1 & 7) * 8;
;   char* ks0 = lds + ((c0 / KCH) * KROW + (c0 % KCH) * 8) * 2;
;   char* ks1 = lds + ((c1 / KCH) * KROW + (c1 % KCH) * 8) * 2;
;   char* ks2 = lds + ((c2 / KCH) * KROW + (c2 % KCH) * 8) * 2;
;   char* vs0 = lds + K_BYTES + ((c0 >> 3) * VROW + (c0 & 7) * 8) * 2;
;   char* vs1 = lds + K_BYTES + ((c1 >> 3) * VROW + (c1 & 7) * 8) * 2;
;     ...
;   bf16x8 qf[NC][KS];
; #pragma unroll
;   for (int c = 0; c < NC; ++c)
; #pragma unroll
;     for (int ks = 0; ks < KS; ++ks) qf[c][ks] = ld8(Qp + (size_t)((SH ? 0 : 16 * c) + jn) * qstride + (SH ? 64 * c : 0) + ks * 32 + q * 8);
;     ...
;   A_LOAD(x, 0);
;   { const int t1 = (nkt_max > 1) ? 1 : 0; A_LOAD(y, t1); }
;   A_STORE(x, 0);
;   __syncthreads();
.LBB0_762:
	s_and_b64 vcc, exec, s[0:1]
	s_cbranch_vccz .LBB0_781
	s_add_i32 s6, s26, 0xf00
	s_not_b32 s1, s26
	s_bfe_u32 s14, s1, 0x50003
	s_lshr_b32 s1, s6, 5
	s_and_b32 s7, s26, 7
	s_and_b32 s1, s1, 0x78
	s_or_b32 s1, s1, s7
	s_mul_i32 s2, s1, 0xab
	s_lshr_b32 s10, s2, 10
	v_readfirstlane_b32 s0, v158
	s_mul_i32 s2, s10, 6
	s_sub_i32 s2, s1, s2
	s_ashr_i32 s0, s0, 1
	s_and_b32 s8, s2, 0xff
	s_lshl_b32 s2, s14, 7
	s_andn2_b32 s0, s0, 31
	s_add_i32 s0, s0, s2
	s_ashr_i32 s9, s0, 6
	s_lshl_b32 s2, s10, 12
	s_ashr_i32 s3, s0, 31
	s_add_u32 s2, s2, s0
	s_addc_u32 s3, 0, s3
	s_mul_i32 s0, s3, 0x480
	s_mul_hi_u32 s4, s2, 0x480
	s_add_i32 s4, s4, s0
	s_mul_i32 s0, s2, 0x480
	s_add_u32 s0, s66, s0
	s_addc_u32 s5, s67, s4
	s_mov_b32 s24, s34
	s_mul_i32 s34, s8, 0xc0
	s_add_u32 s4, s0, s34
	s_addc_u32 s5, s5, 0
	s_mul_i32 s0, s10, 0x480000
	s_add_u32 s10, s68, s0
	s_addc_u32 s11, s69, 0
	s_add_u32 s10, s10, s34
	s_addc_u32 s11, s11, 0
	s_lshl_b32 s1, s1, 19
	v_readlane_b32 s12, v249, 59
	s_add_u32 s12, s12, s1
	v_readlane_b32 s1, v249, 60
	s_addc_u32 s13, s1, 0
	v_add_u32_e32 v0, 0x100, v158
	s_mov_b32 s1, 0x2aaaaaab
	s_waitcnt vmcnt(18)
	v_add_u32_e32 v6, 0x200, v158
	v_mul_hi_i32 v2, v158, s1
	v_mul_hi_i32 v4, v0, s1
	v_lshrrev_b32_e32 v3, 31, v2
	v_ashrrev_i32_e32 v2, 1, v2
	v_lshrrev_b32_e32 v5, 31, v4
	v_ashrrev_i32_e32 v4, 1, v4
	v_mul_hi_i32 v7, v6, s1
	v_add_u32_e32 v96, v2, v3
	v_add_u32_e32 v97, v4, v5
	v_lshrrev_b32_e32 v8, 31, v7
	v_ashrrev_i32_e32 v7, 1, v7
	v_mul_lo_u32 v2, v96, 12
	v_mul_lo_u32 v4, v97, 12
	v_add_u32_e32 v98, v7, v8
	v_bfe_u32 v161, v158, 4, 2
	v_sub_u32_e32 v2, v158, v2
	v_sub_u32_e32 v4, v0, v4
	v_mul_lo_u32 v7, v98, 12
	v_ashrrev_i32_e32 v8, 3, v158
	s_waitcnt vmcnt(13)
	v_ashrrev_i32_e32 v12, 3, v0
	v_and_b32_e32 v160, 15, v158
	v_lshlrev_b32_e32 v0, 4, v161
	v_lshlrev_b32_e32 v2, 3, v2
	v_sub_u32_e32 v6, v6, v7
	v_ashrrev_i32_e32 v9, 31, v8
	v_lshl_add_u64 v[34:35], s[4:5], 0, v[0:1]
	v_mul_u32_u24_e32 v36, 0x480, v160
	v_mov_b32_e32 v37, v1
	v_ashrrev_i32_e32 v3, 31, v2
	v_lshlrev_b32_e32 v4, 3, v4
	v_lshlrev_b32_e32 v6, 3, v6
	v_lshlrev_b64 v[10:11], 13, v[8:9]
	v_lshlrev_b32_e32 v9, 3, v158
	v_ashrrev_i32_e32 v13, 31, v12
	v_mov_b64_e32 v[18:19], s[10:11]
	s_movk_i32 s15, 0x480
	s_waitcnt vmcnt(9)
	v_lshl_add_u64 v[42:43], v[34:35], 0, v[36:37]
	v_ashrrev_i32_e32 v5, 31, v4
	v_ashrrev_i32_e32 v7, 31, v6
	v_and_b32_e32 v9, 56, v9
	v_lshlrev_b64 v[14:15], 13, v[12:13]
	v_mad_i64_i32 v[20:21], s[10:11], v96, s15, v[18:19]
	v_lshlrev_b64 v[66:67], 1, v[2:3]
	v_add_co_u32_e32 v50, vcc, s42, v42
	v_lshl_add_u64 v[16:17], s[12:13], 0, v[14:15]
	v_mad_i64_i32 v[22:23], s[10:11], v97, s15, v[18:19]
	v_mad_i64_i32 v[18:19], s[10:11], v98, s15, v[18:19]
	v_lshl_add_u64 v[24:25], s[12:13], 0, v[10:11]
	v_lshlrev_b32_e32 v26, 1, v9
	v_mov_b32_e32 v27, v1
	v_lshl_add_u64 v[20:21], v[20:21], 0, v[66:67]
	v_lshlrev_b64 v[68:69], 1, v[4:5]
	v_lshlrev_b64 v[94:95], 1, v[6:7]
	v_addc_co_u32_e32 v51, vcc, 0, v43, vcc
	s_mov_b32 s1, 0x12000
	v_lshl_add_u64 v[16:17], v[16:17], 0, v[26:27]
	v_lshl_add_u64 v[22:23], v[22:23], 0, v[68:69]
	v_lshl_add_u64 v[18:19], v[18:19], 0, v[94:95]
	v_lshl_add_u64 v[24:25], v[24:25], 0, v[26:27]
	global_load_dwordx4 v[26:29], v[20:21], off
	global_load_dwordx4 v[30:33], v[22:23], off
	global_load_dwordx4 v[58:61], v[18:19], off
	global_load_dwordx4 v[62:65], v[24:25], off
	global_load_dwordx4 v[78:81], v[16:17], off
	v_add_co_u32_e32 v20, vcc, s1, v20
	s_mov_b64 s[4:5], 0x4800
	s_nop 0
	v_addc_co_u32_e32 v21, vcc, 0, v21, vcc
	v_add_co_u32_e32 v22, vcc, s1, v22
	v_lshl_add_u64 v[54:55], v[42:43], 0, s[4:5]
	s_nop 0
	v_addc_co_u32_e32 v23, vcc, 0, v23, vcc
	v_add_co_u32_e32 v18, vcc, s1, v18
	global_load_dwordx4 v[34:37], v[42:43], off
	global_load_dwordx4 v[38:41], v[42:43], off offset:64
	s_nop 0
	global_load_dwordx4 v[42:45], v[42:43], off offset:128
	s_nop 0
	global_load_dwordx4 v[46:49], v[54:55], off offset:64
	s_nop 0
	global_load_dwordx4 v[50:53], v[50:51], off offset:2048
	s_nop 0
	global_load_dwordx4 v[54:57], v[54:55], off offset:128
	v_addc_co_u32_e32 v19, vcc, 0, v19, vcc
	global_load_dwordx4 v[70:73], v[22:23], off
	global_load_dwordx4 v[82:85], v[18:19], off
	global_load_dwordx4 v[74:77], v[20:21], off
	global_load_dwordx4 v[86:89], v[24:25], off offset:128
	global_load_dwordx4 v[90:93], v[16:17], off offset:128
	s_movk_i32 s4, 0x68
	v_mul_lo_u32 v3, v96, s4
	v_add_lshl_u32 v162, v3, v2, 1
	v_mul_lo_u32 v2, v97, s4
	v_add_lshl_u32 v163, v2, v4, 1
	v_mul_lo_u32 v2, v98, s4
	s_movk_i32 s4, 0x48
	v_add_lshl_u32 v164, v2, v6, 1
	v_mul_lo_u32 v2, v8, s4
	s_mov_b32 s1, s35
	v_add_lshl_u32 v165, v2, v9, 1
	v_mul_lo_u32 v2, v12, s4
	v_add_lshl_u32 v172, v2, v9, 1
	v_and_b32_e32 v246, 1, v158
	v_lshlrev_b32_e32 v246, 4, v246
	v_bfe_u32 v247, v158, 1, 1
	v_mul_u32_u24_e32 v247, 24, v247
	v_sub_u32_e32 v246, v246, v247
	v_add_u32_e32 v242, v165, v246
	v_add_u32_e32 v243, 0x8c00, v242
	v_add_u32_e32 v242, 0x3400, v242
	v_add_u32_e32 v244, v172, v246
	v_add_u32_e32 v245, 0x8c00, v244
	v_add_u32_e32 v244, 0x3400, v244
	v_mov_b64_e32 v[2:3], s[0:1]
	v_mad_i64_i32 v[4:5], s[0:1], v96, s15, v[2:3]
	s_movk_i32 s4, 0xd0
	v_lshl_add_u64 v[4:5], v[4:5], 0, v[66:67]
	v_mad_u32_u24 v173, v160, s4, v0
	v_mul_u32_u24_e32 v0, 0x90, v160
	v_lshl_add_u64 v[136:137], v[4:5], 0, s[34:35]
	v_mad_i64_i32 v[4:5], s[0:1], v97, s15, v[2:3]
	v_mad_i64_i32 v[2:3], s[0:1], v98, s15, v[2:3]
	v_lshl_add_u32 v174, v161, 4, v0
	v_lshlrev_b32_e32 v0, 4, v158
	s_lshl_b32 s1, s6, 14
	v_lshl_add_u64 v[4:5], v[4:5], 0, v[68:69]
	v_lshl_add_u64 v[2:3], v[2:3], 0, v[94:95]
	v_and_b32_e32 v0, 0x70, v0
	s_lshl_b32 s0, s7, 19
	s_and_b32 s1, s1, 0x3c00000
	v_lshl_add_u64 v[138:139], v[4:5], 0, s[34:35]
	v_lshl_add_u64 v[140:141], v[2:3], 0, s[34:35]
	v_or_b32_e32 v10, v10, v0
	s_or_b32 s34, s1, s0
	v_or_b32_e32 v14, v14, v0
	v_mov_b32_e32 v4, v1
	v_mov_b32_e32 v5, v1
	s_lshl_b32 s10, s14, 1
	v_lshl_add_u64 v[142:143], v[10:11], 0, s[34:35]
	v_lshl_add_u64 v[144:145], v[14:15], 0, s[34:35]
	v_mov_b32_e32 v0, v1
	v_mov_b32_e32 v2, v1
	v_mov_b32_e32 v3, v1
	v_mov_b64_e32 v[20:21], v[4:5]
	v_mov_b64_e32 v[8:9], v[4:5]
	v_mov_b64_e32 v[24:25], v[4:5]
	v_mov_b64_e32 v[12:13], v[4:5]
	v_mov_b64_e32 v[68:69], v[4:5]
	v_mov_b64_e32 v[16:17], v[4:5]
	v_mov_b64_e32 v[96:97], v[4:5]
	s_add_i32 s11, s10, 2
	s_mov_b32 s12, 0
	s_mov_b32 s34, s24
	v_mov_b32_e32 v156, 0xff800000
	v_mov_b64_e32 v[18:19], v[2:3]
	v_mov_b64_e32 v[6:7], v[2:3]
	v_mov_b64_e32 v[22:23], v[2:3]
	v_mov_b64_e32 v[10:11], v[2:3]
	v_mov_b64_e32 v[66:67], v[2:3]
	v_mov_b64_e32 v[14:15], v[2:3]
	v_mov_b64_e32 v[94:95], v[2:3]
	v_mov_b32_e32 v157, 0xff800000
	v_mov_b64_e32 v[134:135], v[0:1]
	s_waitcnt vmcnt(15)
	ds_write_b128 v162, v[26:29]
	s_waitcnt vmcnt(14)
	ds_write_b128 v163, v[30:33]
	s_waitcnt vmcnt(13)
	ds_write_b128 v164, v[58:61]
	s_waitcnt vmcnt(12)
	ds_write2_b64 v242, v[62:63], v[64:65] offset1:2
	s_waitcnt vmcnt(11)
	ds_write2_b64 v244, v[78:79], v[80:81] offset1:2
	s_waitcnt lgkmcnt(0)
	s_barrier
	s_branch .LBB0_766
; #define A_STORE(P, buf) { *reinterpret_cast<uint4*>(ks0 + (buf) * BUF_BYTES) = P##k0; *reinterpret_cast<uint4*>(ks1 + (buf) * BUF_BYTES) = P##k1; \
;     if (NKC == 3) *reinterpret_cast<uint4*>(ks2 + (buf) * BUF_BYTES) = P##k2;                                        \
;     *reinterpret_cast<uint4*>(vs0 + (buf) * BUF_BYTES) = P##v0; *reinterpret_cast<uint4*>(vs1 + (buf) * BUF_BYTES) = P##v1; }
; template <int KS, bool MASK, int NC, bool SH>
; DI void attn_block(const u16* Qp, int qstride, const u16* Kp, int kstride, const u16* Vtp, const u64* maskp, int nkt_w, int nkt_max,
;                    const u16* gatep, int gstride, u16* outp, int ostride, char* lds, int tid) {
;     ...
;     if (more) A_STORE(x, 0);
.LBB0_764:
	ds_write_b128 v162, v[26:29]
	ds_write_b128 v163, v[30:33]
	ds_write_b128 v164, v[58:61]
	ds_write2_b64 v242, v[62:63], v[64:65] offset1:2
	ds_write2_b64 v244, v[78:79], v[80:81] offset1:2

; DI unsigned pack2(float a, float b) { return __builtin_bit_cast(unsigned, __builtin_convertvector((f32x2_t){a, b}, bf16x2_t)); }
; DI f32x4 mfma16(bf16x8 a, bf16x8 b, f32x4 c) { return __builtin_amdgcn_mfma_f32_16x16x32_bf16(a, b, c, 0, 0, 0); }
; DI float fexp2(float x) { return __builtin_amdgcn_exp2f(x); }
; template <int KS, bool MASK, int NC, bool SH>
; DI void attn_block(const u16* Qp, int qstride, const u16* Kp, int kstride, const u16* Vtp, const u64* maskp, int nkt_w, int nkt_max,
;                    const u16* gatep, int gstride, u16* outp, int ostride, char* lds, int tid) {
;     ...
;       float ps = 0.f;
; #pragma unroll
;       for (int a = 0; a < 4; ++a)
; #pragma unroll
;         for (int r = 0; r < 4; ++r) { float p = fexp2(s[a][c][r] - mu); s[a][c][r] = p; ps += p; }
;       lsum[c] = lsum[c] * alpha[c] + ps;
;     }
;     bool resc = false;
; #pragma unroll
;     for (int c = 0; c < NC; ++c) resc = resc || (alpha[c] != 1.0f);
;     if (__builtin_amdgcn_ballot_w64(resc) != 0ull) {
; #pragma unroll
;       for (int c = 0; c < NC; ++c)
; #pragma unroll
;         for (int dt = 0; dt < 4; ++dt)
; #pragma unroll
;           for (int r = 0; r < 4; ++r) o[dt][c][r] *= alpha[c];
;     }
; #pragma unroll
;     for (int kk = 0; kk < 2; ++kk) {
;       bf16x8 pf[NC];
; #pragma unroll
;       for (int c = 0; c < NC; ++c) {
;         uint4 w; w.x = pack2(s[2 * kk][c][0], s[2 * kk][c][1]); w.y = pack2(s[2 * kk][c][2], s[2 * kk][c][3]);
;         w.z = pack2(s[2 * kk + 1][c][0], s[2 * kk + 1][c][1]); w.w = pack2(s[2 * kk + 1][c][2], s[2 * kk + 1][c][3]);
;         pf[c] = __builtin_bit_cast(bf16x8, w);
;       }
; #pragma unroll
;       for (int dt = 0; dt < 4; ++dt) {
;         const char* vp = vb + ((16 * dt + jn) * VROW + kk * 32 + 4 * q) * 2;
;         const uint2 lo = *reinterpret_cast<const uint2*>(vp), hi = *reinterpret_cast<const uint2*>(vp + 32);
;         uint4 w; w.x = lo.x; w.y = lo.y; w.z = hi.x; w.w = hi.y;
;         const bf16x8 vf = __builtin_bit_cast(bf16x8, w);
; #pragma unroll
;         for (int c = 0; c < NC; ++c) o[dt][c] = mfma16(vf, pf[c], o[dt][c]);
;       }
;     }
.LBB0_771:
	v_sub_f32_e32 v110, v110, v176
	v_exp_f32_e32 v179, v110
	v_sub_f32_e32 v110, v111, v176
	v_exp_f32_e32 v181, v110
	v_sub_f32_e32 v110, v112, v176
	v_exp_f32_e32 v183, v110
	v_sub_f32_e32 v110, v113, v176
	v_exp_f32_e32 v185, v110
	v_sub_f32_e32 v110, v118, v176
	v_exp_f32_e32 v187, v110
	v_sub_f32_e32 v110, v119, v176
	v_exp_f32_e32 v189, v110
	v_sub_f32_e32 v110, v120, v176
	v_exp_f32_e32 v191, v110
	v_sub_f32_e32 v110, v121, v176
	v_sub_f32_e32 v98, v98, v177
	v_exp_f32_e32 v193, v110
	v_sub_f32_e32 v110, v122, v176
	v_exp_f32_e32 v178, v98
	v_sub_f32_e32 v98, v99, v177
	v_exp_f32_e32 v111, v110
	v_sub_f32_e32 v110, v123, v176
	v_exp_f32_e32 v180, v98
	v_sub_f32_e32 v98, v100, v177
	v_exp_f32_e32 v113, v110
	v_sub_f32_e32 v110, v124, v176
	v_exp_f32_e32 v182, v98
	v_sub_f32_e32 v98, v101, v177
	v_exp_f32_e32 v119, v110
	v_sub_f32_e32 v110, v125, v176
	v_exp_f32_e32 v184, v98
	v_sub_f32_e32 v98, v102, v177
	v_exp_f32_e32 v121, v110
	v_sub_f32_e32 v110, v126, v176
	v_exp_f32_e32 v186, v98
	v_sub_f32_e32 v98, v103, v177
	v_exp_f32_e32 v123, v110
	v_sub_f32_e32 v110, v127, v176
	v_exp_f32_e32 v188, v98
	v_sub_f32_e32 v98, v104, v177
	v_exp_f32_e32 v125, v110
	v_sub_f32_e32 v110, v128, v176
	v_exp_f32_e32 v190, v98
	v_sub_f32_e32 v98, v105, v177
	v_exp_f32_e32 v127, v110
	v_sub_f32_e32 v110, v129, v176
	v_exp_f32_e32 v192, v98
	v_sub_f32_e32 v98, v106, v177
	v_exp_f32_e32 v129, v110
	v_exp_f32_e32 v110, v98
	v_pk_add_f32 v[98:99], v[178:179], 0 op_sel_hi:[1,0]
	v_sub_f32_e32 v100, v107, v177
	v_pk_add_f32 v[98:99], v[180:181], v[98:99]
	v_exp_f32_e32 v112, v100
	v_pk_add_f32 v[98:99], v[182:183], v[98:99]
	v_sub_f32_e32 v100, v108, v177
	v_pk_add_f32 v[98:99], v[184:185], v[98:99]
	v_exp_f32_e32 v118, v100
	v_pk_add_f32 v[98:99], v[186:187], v[98:99]
	v_sub_f32_e32 v100, v109, v177
	v_pk_add_f32 v[98:99], v[188:189], v[98:99]
	v_exp_f32_e32 v120, v100
	v_pk_add_f32 v[98:99], v[190:191], v[98:99]
	v_sub_f32_e32 v100, v114, v177
	v_pk_add_f32 v[98:99], v[192:193], v[98:99]
	v_add_u32_e32 v114, 0x3000, v174
	v_pk_add_f32 v[98:99], v[110:111], v[98:99]
	v_exp_f32_e32 v122, v100
	v_sub_f32_e32 v100, v115, v177
	ds_read_b128 v[106:109], v114 offset:1024
	v_exp_f32_e32 v124, v100
	v_sub_f32_e32 v100, v116, v177
	v_pk_add_f32 v[98:99], v[112:113], v[98:99]
	v_exp_f32_e32 v126, v100
	v_sub_f32_e32 v100, v117, v177
	v_pk_add_f32 v[98:99], v[118:119], v[98:99]
	v_exp_f32_e32 v128, v100
	v_pk_add_f32 v[98:99], v[120:121], v[98:99]
	v_cvt_pk_bf16_f32 v100, v187, v189
	v_pk_add_f32 v[98:99], v[122:123], v[98:99]
	v_cvt_pk_bf16_f32 v101, v191, v193
	v_pk_add_f32 v[98:99], v[124:125], v[98:99]
	v_cvt_pk_bf16_f32 v102, v178, v180
	v_pk_add_f32 v[98:99], v[126:127], v[98:99]
	v_cvt_pk_bf16_f32 v103, v182, v184
	v_pk_add_f32 v[98:99], v[128:129], v[98:99]
	v_cvt_pk_bf16_f32 v104, v186, v188
	v_pk_fma_f32 v[134:135], v[134:135], v[156:157], v[98:99]
	v_cvt_pk_bf16_f32 v98, v179, v181
	v_cvt_pk_bf16_f32 v99, v183, v185
	v_cvt_pk_bf16_f32 v105, v190, v192
	v_add_u32_e32 v115, 0x3800, v174
	s_waitcnt lgkmcnt(0)
	v_mfma_f32_16x16x32_bf16 v[94:97], v[106:109], v[98:101], v[94:97]
	v_add_u32_e32 v116, 0x4000, v174
	v_add_u32_e32 v117, 0x4800, v174
	v_mfma_f32_16x16x32_bf16 v[14:17], v[106:109], v[102:105], v[14:17]
	ds_read_b128 v[106:109], v115 offset:1280
	s_waitcnt lgkmcnt(0)
	v_mfma_f32_16x16x32_bf16 v[66:69], v[106:109], v[98:101], v[66:69]
	v_mfma_f32_16x16x32_bf16 v[10:13], v[106:109], v[102:105], v[10:13]
	ds_read_b128 v[106:109], v116 offset:1536
	s_waitcnt lgkmcnt(0)
	v_mfma_f32_16x16x32_bf16 v[22:25], v[106:109], v[98:101], v[22:25]
	v_mfma_f32_16x16x32_bf16 v[6:9], v[106:109], v[102:105], v[6:9]
	ds_read_b128 v[106:109], v117 offset:1792
	s_waitcnt lgkmcnt(0)
	v_mfma_f32_16x16x32_bf16 v[18:21], v[106:109], v[98:101], v[18:21]
	v_cvt_pk_bf16_f32 v98, v111, v113
	v_cvt_pk_bf16_f32 v99, v119, v121
	v_cvt_pk_bf16_f32 v100, v123, v125
	v_mfma_f32_16x16x32_bf16 v[2:5], v[106:109], v[102:105], v[2:5]
	ds_read_b128 v[106:109], v114 offset:1088
	v_cvt_pk_bf16_f32 v101, v127, v129
	v_cvt_pk_bf16_f32 v102, v110, v112
	v_cvt_pk_bf16_f32 v103, v118, v120
	v_cvt_pk_bf16_f32 v104, v122, v124
	v_cvt_pk_bf16_f32 v105, v126, v128
	s_waitcnt lgkmcnt(0)
	v_mfma_f32_16x16x32_bf16 v[94:97], v[106:109], v[98:101], v[94:97]
	v_mfma_f32_16x16x32_bf16 v[14:17], v[106:109], v[102:105], v[14:17]
	ds_read_b128 v[106:109], v115 offset:1344
	s_waitcnt lgkmcnt(0)
	v_mfma_f32_16x16x32_bf16 v[66:69], v[106:109], v[98:101], v[66:69]
	v_mfma_f32_16x16x32_bf16 v[10:13], v[106:109], v[102:105], v[10:13]
	ds_read_b128 v[106:109], v116 offset:1600
	s_waitcnt lgkmcnt(0)
	v_mfma_f32_16x16x32_bf16 v[22:25], v[106:109], v[98:101], v[22:25]
	v_mfma_f32_16x16x32_bf16 v[6:9], v[106:109], v[102:105], v[6:9]
	ds_read_b128 v[106:109], v117 offset:1856
	s_waitcnt lgkmcnt(0)
	v_mfma_f32_16x16x32_bf16 v[18:21], v[106:109], v[98:101], v[18:21]
	v_mfma_f32_16x16x32_bf16 v[2:5], v[106:109], v[102:105], v[2:5]
	s_branch .LBB0_773

; #define A_STORE(P, buf) { *reinterpret_cast<uint4*>(ks0 + (buf) * BUF_BYTES) = P##k0; *reinterpret_cast<uint4*>(ks1 + (buf) * BUF_BYTES) = P##k1; \
;     if (NKC == 3) *reinterpret_cast<uint4*>(ks2 + (buf) * BUF_BYTES) = P##k2;                                        \
;     *reinterpret_cast<uint4*>(vs0 + (buf) * BUF_BYTES) = P##v0; *reinterpret_cast<uint4*>(vs1 + (buf) * BUF_BYTES) = P##v1; }
; template <int KS, bool MASK, int NC, bool SH>
; DI void attn_block(const u16* Qp, int qstride, const u16* Kp, int kstride, const u16* Vtp, const u64* maskp, int nkt_w, int nkt_max,
;                    const u16* gatep, int gstride, u16* outp, int ostride, char* lds, int tid) {
;     ...
;     A_STORE(y, 1);
;     __syncthreads();
;     if (kt + 3 < nkt_max) A_LOAD(y, kt + 3);
.LBB0_773:
	s_add_i32 s0, s12, 3
	s_cmp_ge_u32 s0, s11
	s_waitcnt vmcnt(2)
	ds_write_b128 v162, v[74:77] offset:22528
	ds_write_b128 v163, v[70:73] offset:22528
	ds_write_b128 v164, v[82:85] offset:22528
	s_waitcnt vmcnt(1)
	ds_write2_b64 v243, v[86:87], v[88:89] offset1:2
	s_waitcnt vmcnt(0)
	ds_write2_b64 v245, v[90:91], v[92:93] offset1:2
	s_waitcnt lgkmcnt(0)
	s_barrier
	s_cbranch_scc1 .LBB0_775
	v_add_co_u32_e32 v70, vcc, 0x24cc6000, v154
	s_nop 1
	v_addc_co_u32_e32 v71, vcc, 0, v155, vcc
	v_add_co_u32_e32 v72, vcc, 0x24cc6000, v152
	s_nop 1
	v_addc_co_u32_e32 v73, vcc, 0, v153, vcc
	v_add_co_u32_e32 v82, vcc, 0x24cc6000, v150
	global_load_dwordx4 v[74:77], v[70:71], off
	s_nop 0
	global_load_dwordx4 v[70:73], v[72:73], off
	v_addc_co_u32_e32 v83, vcc, 0, v151, vcc
	v_add_co_u32_e32 v86, vcc, 0x29490000, v148
	s_nop 1
	v_addc_co_u32_e32 v87, vcc, 0, v149, vcc
	v_add_co_u32_e32 v90, vcc, 0x29490000, v146
	global_load_dwordx4 v[82:85], v[82:83], off
	s_nop 0
	global_load_dwordx4 v[86:89], v[86:87], off offset:384
	v_addc_co_u32_e32 v91, vcc, 0, v147, vcc
	global_load_dwordx4 v[90:93], v[90:91], off offset:384

; DI unsigned pack2(float a, float b) { return __builtin_bit_cast(unsigned, __builtin_convertvector((f32x2_t){a, b}, bf16x2_t)); }
; DI f32x4 mfma16(bf16x8 a, bf16x8 b, f32x4 c) { return __builtin_amdgcn_mfma_f32_16x16x32_bf16(a, b, c, 0, 0, 0); }
; DI float fexp2(float x) { return __builtin_amdgcn_exp2f(x); }
; template <int KS, bool MASK, int NC, bool SH>
; DI void attn_block(const u16* Qp, int qstride, const u16* Kp, int kstride, const u16* Vtp, const u64* maskp, int nkt_w, int nkt_max,
;                    const u16* gatep, int gstride, u16* outp, int ostride, char* lds, int tid) {
;     ...
;       float ps = 0.f;
; #pragma unroll
;       for (int a = 0; a < 4; ++a)
; #pragma unroll
;         for (int r = 0; r < 4; ++r) { float p = fexp2(s[a][c][r] - mu); s[a][c][r] = p; ps += p; }
;       lsum[c] = lsum[c] * alpha[c] + ps;
;     }
;     bool resc = false;
; #pragma unroll
;     for (int c = 0; c < NC; ++c) resc = resc || (alpha[c] != 1.0f);
;     if (__builtin_amdgcn_ballot_w64(resc) != 0ull) {
; #pragma unroll
;       for (int c = 0; c < NC; ++c)
; #pragma unroll
;         for (int dt = 0; dt < 4; ++dt)
; #pragma unroll
;           for (int r = 0; r < 4; ++r) o[dt][c][r] *= alpha[c];
;     }
; #pragma unroll
;     for (int kk = 0; kk < 2; ++kk) {
;       bf16x8 pf[NC];
; #pragma unroll
;       for (int c = 0; c < NC; ++c) {
;         uint4 w; w.x = pack2(s[2 * kk][c][0], s[2 * kk][c][1]); w.y = pack2(s[2 * kk][c][2], s[2 * kk][c][3]);
;         w.z = pack2(s[2 * kk + 1][c][0], s[2 * kk + 1][c][1]); w.w = pack2(s[2 * kk + 1][c][2], s[2 * kk + 1][c][3]);
;         pf[c] = __builtin_bit_cast(bf16x8, w);
;       }
; #pragma unroll
;       for (int dt = 0; dt < 4; ++dt) {
;         const char* vp = vb + ((16 * dt + jn) * VROW + kk * 32 + 4 * q) * 2;
;         const uint2 lo = *reinterpret_cast<const uint2*>(vp), hi = *reinterpret_cast<const uint2*>(vp + 32);
;         uint4 w; w.x = lo.x; w.y = lo.y; w.z = hi.x; w.w = hi.y;
;         const bf16x8 vf = __builtin_bit_cast(bf16x8, w);
; #pragma unroll
;         for (int c = 0; c < NC; ++c) o[dt][c] = mfma16(vf, pf[c], o[dt][c]);
;       }
;     }
.LBB0_778:
	v_sub_f32_e32 v114, v114, v148
	v_exp_f32_e32 v149, v114
	v_sub_f32_e32 v114, v115, v148
	v_exp_f32_e32 v151, v114
	v_sub_f32_e32 v114, v116, v148
	v_exp_f32_e32 v153, v114
	v_sub_f32_e32 v114, v117, v148
	v_exp_f32_e32 v155, v114
	v_sub_f32_e32 v114, v118, v148
	v_exp_f32_e32 v177, v114
	v_sub_f32_e32 v114, v119, v148
	v_exp_f32_e32 v179, v114
	v_sub_f32_e32 v114, v120, v148
	v_exp_f32_e32 v181, v114
	v_sub_f32_e32 v114, v121, v148
	v_exp_f32_e32 v183, v114
	v_sub_f32_e32 v114, v122, v148
	v_exp_f32_e32 v115, v114
	v_sub_f32_e32 v114, v123, v148
	v_exp_f32_e32 v117, v114
	v_sub_f32_e32 v114, v124, v148
	v_exp_f32_e32 v119, v114
	v_sub_f32_e32 v114, v125, v148
	v_exp_f32_e32 v121, v114
	v_sub_f32_e32 v114, v126, v148
	v_exp_f32_e32 v123, v114
	v_sub_f32_e32 v114, v127, v148
	v_exp_f32_e32 v125, v114
	v_sub_f32_e32 v114, v128, v148
	v_sub_f32_e32 v106, v106, v0
	v_exp_f32_e32 v127, v114
	v_sub_f32_e32 v114, v129, v148
	v_exp_f32_e32 v148, v106
	v_sub_f32_e32 v106, v107, v0
	v_exp_f32_e32 v150, v106
	v_sub_f32_e32 v106, v108, v0
	v_exp_f32_e32 v152, v106
	v_sub_f32_e32 v106, v109, v0
	v_sub_f32_e32 v98, v98, v0
	v_sub_f32_e32 v100, v100, v0
	v_exp_f32_e32 v154, v106
	v_exp_f32_e32 v176, v98
	v_sub_f32_e32 v98, v99, v0
	v_exp_f32_e32 v180, v100
	v_sub_f32_e32 v100, v101, v0
	v_exp_f32_e32 v178, v98
	v_pk_add_f32 v[98:99], v[148:149], 0 op_sel_hi:[1,0]
	v_exp_f32_e32 v182, v100
	v_sub_f32_e32 v100, v102, v0
	v_exp_f32_e32 v129, v114
	v_pk_add_f32 v[98:99], v[150:151], v[98:99]
	v_exp_f32_e32 v114, v100
	v_sub_f32_e32 v100, v103, v0
	v_pk_add_f32 v[98:99], v[152:153], v[98:99]
	v_exp_f32_e32 v116, v100
	v_sub_f32_e32 v100, v104, v0
	v_pk_add_f32 v[98:99], v[154:155], v[98:99]
	v_exp_f32_e32 v118, v100
	v_sub_f32_e32 v100, v105, v0
	v_pk_add_f32 v[98:99], v[176:177], v[98:99]
	v_exp_f32_e32 v120, v100
	v_sub_f32_e32 v100, v110, v0
	v_pk_add_f32 v[98:99], v[178:179], v[98:99]
	v_exp_f32_e32 v122, v100
	v_sub_f32_e32 v100, v111, v0
	v_exp_f32_e32 v124, v100
	v_sub_f32_e32 v100, v112, v0
	v_sub_f32_e32 v0, v113, v0
	v_pk_add_f32 v[98:99], v[180:181], v[98:99]
	v_exp_f32_e32 v128, v0
	v_pk_add_f32 v[98:99], v[182:183], v[98:99]
	v_add_u32_e32 v0, 0x8800, v174
	v_pk_add_f32 v[98:99], v[114:115], v[98:99]
	ds_read_b128 v[106:109], v0 offset:1024
	v_pk_add_f32 v[98:99], v[116:117], v[98:99]
	v_exp_f32_e32 v126, v100
	v_pk_add_f32 v[98:99], v[118:119], v[98:99]
	v_cvt_pk_bf16_f32 v100, v177, v179
	v_pk_add_f32 v[98:99], v[120:121], v[98:99]
	v_cvt_pk_bf16_f32 v101, v181, v183
	v_pk_add_f32 v[98:99], v[122:123], v[98:99]
	v_cvt_pk_bf16_f32 v102, v148, v150
	v_pk_add_f32 v[98:99], v[124:125], v[98:99]
	v_cvt_pk_bf16_f32 v103, v152, v154
	v_pk_add_f32 v[98:99], v[126:127], v[98:99]
	v_cvt_pk_bf16_f32 v104, v176, v178
	v_pk_add_f32 v[98:99], v[128:129], v[98:99]
	v_cvt_pk_bf16_f32 v105, v180, v182
	v_pk_fma_f32 v[134:135], v[134:135], v[146:147], v[98:99]
	v_cvt_pk_bf16_f32 v98, v149, v151
	v_cvt_pk_bf16_f32 v99, v153, v155
	v_add_u32_e32 v110, 0x9000, v174
	s_waitcnt lgkmcnt(0)
	v_mfma_f32_16x16x32_bf16 v[14:17], v[106:109], v[102:105], v[14:17]
	v_add_u32_e32 v111, 0x9800, v174
	v_add_u32_e32 v112, 0xa000, v174
	v_mfma_f32_16x16x32_bf16 v[94:97], v[106:109], v[98:101], v[94:97]
	ds_read_b128 v[106:109], v110 offset:1280
	s_waitcnt lgkmcnt(0)
	v_mfma_f32_16x16x32_bf16 v[66:69], v[106:109], v[98:101], v[66:69]
	v_mfma_f32_16x16x32_bf16 v[10:13], v[106:109], v[102:105], v[10:13]
	ds_read_b128 v[106:109], v111 offset:1536
	s_waitcnt lgkmcnt(0)
	v_mfma_f32_16x16x32_bf16 v[22:25], v[106:109], v[98:101], v[22:25]
	v_mfma_f32_16x16x32_bf16 v[6:9], v[106:109], v[102:105], v[6:9]
	ds_read_b128 v[106:109], v112 offset:1792
	s_waitcnt lgkmcnt(0)
	v_mfma_f32_16x16x32_bf16 v[18:21], v[106:109], v[98:101], v[18:21]
	v_cvt_pk_bf16_f32 v98, v115, v117
	v_cvt_pk_bf16_f32 v99, v119, v121
	v_cvt_pk_bf16_f32 v100, v123, v125
	v_mfma_f32_16x16x32_bf16 v[2:5], v[106:109], v[102:105], v[2:5]
	ds_read_b128 v[106:109], v0 offset:1088
	v_cvt_pk_bf16_f32 v101, v127, v129
	v_cvt_pk_bf16_f32 v102, v114, v116
	v_cvt_pk_bf16_f32 v103, v118, v120
	v_cvt_pk_bf16_f32 v104, v122, v124
	v_cvt_pk_bf16_f32 v105, v126, v128
	s_waitcnt lgkmcnt(0)
	v_mfma_f32_16x16x32_bf16 v[94:97], v[106:109], v[98:101], v[94:97]
	v_mfma_f32_16x16x32_bf16 v[14:17], v[106:109], v[102:105], v[14:17]
	ds_read_b128 v[106:109], v110 offset:1344
	s_waitcnt lgkmcnt(0)
	v_mfma_f32_16x16x32_bf16 v[66:69], v[106:109], v[98:101], v[66:69]
	v_mfma_f32_16x16x32_bf16 v[10:13], v[106:109], v[102:105], v[10:13]
	ds_read_b128 v[106:109], v111 offset:1600
	s_waitcnt lgkmcnt(0)
	v_mfma_f32_16x16x32_bf16 v[22:25], v[106:109], v[98:101], v[22:25]
	v_mfma_f32_16x16x32_bf16 v[6:9], v[106:109], v[102:105], v[6:9]
	ds_read_b128 v[106:109], v112 offset:1856
	s_waitcnt lgkmcnt(0)
	v_mfma_f32_16x16x32_bf16 v[18:21], v[106:109], v[98:101], v[18:21]
	v_mfma_f32_16x16x32_bf16 v[2:5], v[106:109], v[102:105], v[2:5]
	s_andn2_b64 vcc, exec, s[6:7]
	s_cbranch_vccnz .LBB0_765
	s_branch .LBB0_764
